# mov64: accumulator hand-over at the bottom of the selected/window loops with 8 v_mov_b64 instead of 16 v_mov_b32
# speedup vs baseline: 1.0146x; 1.0146x over previous
.Lsel_skip_pf:
	s_waitcnt lgkmcnt(0)
	s_barrier
	s_mov_b32 s32, s89
	s_mov_b32 s97, s91
	s_mov_b32 s89, s98
	s_mov_b32 s91, s99
	s_add_i32 s0, s83, 2
	s_add_i32 s1, s83, -2
	s_cmp_lt_u32 s1, s79
	s_cbranch_scc0 .LBB0_1051
	v_mov_b64_e32 v[32:33], v[80:81]
	s_mov_b32 s83, s0
	v_mov_b64_e32 v[34:35], v[82:83]
	v_mov_b64_e32 v[36:37], v[0:1]
	v_mov_b64_e32 v[38:39], v[2:3]
	v_mov_b64_e32 v[40:41], v[4:5]
	v_mov_b64_e32 v[42:43], v[6:7]
	v_mov_b64_e32 v[44:45], v[8:9]
	v_mov_b64_e32 v[46:47], v[10:11]
	v_mov_b64_e32 v[84:85], v[12:13]
	v_mov_b64_e32 v[86:87], v[14:15]
	s_branch .LBB0_1040

.Lwin_skip_pf:
	s_waitcnt lgkmcnt(0)
	s_barrier
	s_add_i32 s1, s23, 2
	s_add_i32 s23, s23, -3
	s_cmp_lt_i32 s23, s21
	v_add_u32_e32 v81, 0xffffff80, v81
	s_cbranch_scc0 .LBB0_1069
	v_mov_b64_e32 v[88:89], v[84:85]
	s_mov_b32 s24, s0
	s_mov_b32 s23, s1
	v_mov_b64_e32 v[86:87], v[82:83]
	v_mov_b64_e32 v[90:91], v[16:17]
	v_mov_b64_e32 v[92:93], v[18:19]
	v_mov_b64_e32 v[94:95], v[20:21]
	v_mov_b64_e32 v[96:97], v[22:23]
	v_mov_b64_e32 v[98:99], v[24:25]
	v_mov_b64_e32 v[100:101], v[26:27]
	v_mov_b64_e32 v[102:103], v[28:29]
	v_mov_b64_e32 v[104:105], v[30:31]
	s_branch .LBB0_1061
